# c13 + the 8 'bv' column tiles also computed with exchanged operand panels; hand-written fragment-major store path (a lane's 16 bytes = 8 tokens of one feature), no LDS transposes left in the in-projec
# baseline (speedup 1.0000x reference)
; #define PG8_STAGE(bufoff, gbase, voff) do { _Pragma("unroll") for (int _i = 0; _i < 2; ++_i) \
;         __builtin_amdgcn_global_load_lds((const unsigned*)((const char*)(gbase) + (voff)[_i]), (PG8_LAS unsigned*)(lds + (bufoff) + ldsw + _i * 8192), 16, 0, 0); } while (0)
; #define PG8_WAIT_V(n) asm volatile("s_waitcnt vmcnt(" #n ")" ::: "memory")
; #define PG8_BAR __builtin_amdgcn_s_barrier()
; template <class Epi, class Sched, bool ALIGN_EPI = false, bool SP2 = false>
; __device__ __forceinline__ void gemm_phase(PG8_LAS unsigned char* lds, const Gemm g, const Sched& S, const Epi& E) {
;     ...
;     const char* cA = (const char*)g.A + (size_t)cur.pm * tstep; const char* cB = (const char*)g.Bt + (size_t)cur.pn * tstep;
;     S.a_ready(cur);
;     if constexpr (SP2) {
;         PG8_STAGE(PG8_SB(0, 0), cB, voffB); PG8_STAGE(PG8_SB(0, 1), cB + hstep, voffB); PG8_STAGE(PG8_SA(0, 0), cA, voffA); PG8_STAGE(PG8_SA(0, 1), cA + hstep, voffA);
;         if (wr == 1) PG8_BAR;
;         PG8_WAIT_V(2); PG8_BAR;
;         PG8_STAGE(PG8_SB(1, 0), cB + kstep, voffB); PG8_STAGE(PG8_SA(1, 0), cA + kstep, voffA); PG8_STAGE(PG8_SB(1, 1), cB + hstep + kstep, voffB);
;         PG8_WAIT_V(6); PG8_BAR;
;     } else {
;         PG8_STAGE(PG8_SB(0, 0), cB, voffB); PG8_STAGE(PG8_SA(0, 0), cA, voffA); PG8_STAGE(PG8_SB(0, 1), cB + hstep, voffB); PG8_STAGE(PG8_SA(0, 1), cA + hstep, voffA);
;         if (wr == 1) PG8_BAR;
;         PG8_WAIT_V(4); PG8_BAR;
.LBB0_175:
	v_readlane_b32 s10, v252, 0
	v_readlane_b32 s11, v252, 1
	s_load_dword s46, s[10:11], 0x98
	s_andn2_b64 vcc, exec, s[4:5]
	s_cbranch_vccnz .LBB0_272
	v_lshrrev_b32_e32 v2, 1, v161
	v_lshrrev_b32_e32 v3, 5, v161
	v_and_b32_e32 v2, 24, v2
	v_and_b32_e32 v3, 4, v3
	v_bfe_u32 v4, v161, 2, 2
	v_lshlrev_b32_e32 v0, 4, v161
	v_and_b32_e32 v1, 32, v161
	v_bfe_u32 v10, v161, 2, 4
	v_or3_b32 v2, v3, v4, v2
	v_lshrrev_b32_e32 v3, 3, v161
	s_movk_i32 s4, 0x70
	v_bitop3_b32 v8, v0, v1, 48 bitop3:0x6c
	v_and_b32_e32 v9, 64, v161
	v_and_or_b32 v4, v3, s4, v10
	s_movk_i32 s4, 0x60
	v_add_u32_e32 v11, 0x2000, v0
	s_add_u32 s47, s92, 0x8200000
	v_or_b32_e32 v1, v8, v9
	v_and_or_b32 v3, v3, s4, v2
	v_lshrrev_b32_e32 v0, 7, v11
	s_movk_i32 s4, 0xf0
	s_addc_u32 s48, s93, 0
	s_lshr_b32 s3, s1, 6
	v_lshl_or_b32 v136, v3, 12, v1
	v_and_or_b32 v3, v0, s4, v10
	s_movk_i32 s4, 0xe0
	s_ashr_i32 s13, s12, 31
	s_ashr_i32 s7, s6, 31
	v_and_or_b32 v0, v0, s4, v2
	s_lshr_b32 s4, s1, 8
	s_lshl_b32 s49, s3, 10
	s_lshl_b64 s[10:11], s[12:13], 20
	s_lshl_b64 s[14:15], s[6:7], 20
	s_add_u32 s42, s47, s14
	s_addc_u32 s43, s48, s15
	s_add_u32 s40, s92, s10
	s_addc_u32 s41, s93, s11
	s_and_b32 s32, s6, -4
	s_cmp_eq_u32 s32, 8
	s_cselect_b32 s32, 1, 0
	s_and_b32 s10, s6, -8
	s_cmp_eq_u32 s10, 24
	s_cselect_b32 s32, 1, s32
	s_cmp_lg_u32 s32, 0
	s_cselect_b32 s32, s42, s40
	s_cselect_b32 s10, s43, s41
	s_cselect_b32 s42, s40, s42
	s_cselect_b32 s43, s41, s43
	s_mov_b32 s40, s32
	s_mov_b32 s41, s10
	s_add_i32 s50, s49, 0
	s_add_i32 m0, s50, 0x10000
	v_lshl_or_b32 v140, v0, 12, v1
	global_load_lds_dwordx4 v136, s[42:43]
	s_add_i32 m0, s50, 0x12000
	s_add_u32 s14, s42, 0x80000
	global_load_lds_dwordx4 v140, s[42:43]
	s_addc_u32 s15, s43, 0
	s_add_i32 m0, s50, 0x14000
	v_lshl_or_b32 v134, v4, 12, v1
	global_load_lds_dwordx4 v136, s[14:15]
	s_add_i32 m0, s50, 0x16000


; #define PG8_STAGE(bufoff, gbase, voff) do { _Pragma("unroll") for (int _i = 0; _i < 2; ++_i) \
;         __builtin_amdgcn_global_load_lds((const unsigned*)((const char*)(gbase) + (voff)[_i]), (PG8_LAS unsigned*)(lds + (bufoff) + ldsw + _i * 8192), 16, 0, 0); } while (0)
; #define PG8_BAR __builtin_amdgcn_s_barrier()
; template <class Epi, class Sched, bool ALIGN_EPI = false, bool SP2 = false>
; __device__ __forceinline__ void gemm_phase(PG8_LAS unsigned char* lds, const Gemm g, const Sched& S, const Epi& E) {
;     ...
;         PG8_STAGE(PG8_SB(0, 0), cB, voffB); PG8_STAGE(PG8_SA(0, 0), cA, voffA); PG8_STAGE(PG8_SB(0, 1), cB + hstep, voffB); PG8_STAGE(PG8_SA(0, 1), cA + hstep, voffA);
;         if (wr == 1) PG8_BAR;
	s_add_i32 s51, s50, 0x2000
	global_load_lds_dwordx4 v140, s[14:15]
	s_mov_b32 m0, s50
	s_add_u32 s10, s40, 0x80000
	v_lshl_or_b32 v138, v3, 12, v1
	global_load_lds_dwordx4 v134, s[40:41]
	s_mov_b32 m0, s51
	s_addc_u32 s11, s41, 0
	s_add_i32 s52, s50, 0x4000
	global_load_lds_dwordx4 v138, s[40:41]
	s_mov_b32 m0, s52
	s_add_i32 s53, s50, 0x6000
	global_load_lds_dwordx4 v134, s[10:11]
	s_mov_b32 m0, s53
	v_mov_b32_e32 v143, 0
	global_load_lds_dwordx4 v138, s[10:11]
	v_mov_b32_e32 v137, v143
	v_mov_b32_e32 v141, v143
	v_mov_b32_e32 v135, v143
	v_mov_b32_e32 v139, v143
	s_cmp_eq_u32 s4, 1
	s_mov_b32 s11, 0
	v_lshl_add_u64 v[6:7], s[42:43], 0, v[136:137]
	v_lshl_add_u64 v[4:5], s[42:43], 0, v[140:141]
	v_lshl_add_u64 v[2:3], s[40:41], 0, v[134:135]
	v_lshl_add_u64 v[0:1], s[40:41], 0, v[138:139]
	s_cselect_b64 s[14:15], -1, 0
	s_cmp_lg_u32 s4, 1
	s_movk_i32 s54, 0x4000
	s_cbranch_scc1 .LBB0_178
	s_barrier

; template <class Epi, class Sched, bool ALIGN_EPI = false, bool SP2 = false>
; __device__ __forceinline__ void gemm_phase(PG8_LAS unsigned char* lds, const Gemm g, const Sched& S, const Epi& E) {
;     ...
;         const bool has_next = S.next(ui + 1, nxt);
;         const char* nA = has_next ? (const char*)g.A + (size_t)nxt.pm * tstep : cA; const char* nB = has_next ? (const char*)g.Bt + (size_t)nxt.pn * tstep : cB;
;     ...
; #pragma unroll
;         for (int a = 0; a < 2; ++a)
; #pragma unroll
;             for (int b = 0; b < 2; ++b)
; #pragma unroll
;                 for (int m = 0; m < 4; ++m)
; #pragma unroll
;                     for (int n = 0; n < 2; ++n) acc[a][b][m][n] = (f32x4){0.f, 0.f, 0.f, 0.f};
;         cur = nxt; cA = nA; cB = nB; ++ui;
.LBB0_187:
	s_cmp_lg_u32 s6, 56
	s_cselect_b32 s32, 1, 0
	s_and_b32 vcc_lo, s0, 3
	s_lshl_b32 vcc_lo, vcc_lo, 12
	s_mul_i32 vcc_lo, vcc_lo, s32
	s_mulk_i32 s32, 0x3000
	s_sub_i32 s32, vcc_lo, s32
	v_add_u32_e32 v177, vcc_lo, v159
	v_add_u32_e32 v244, s32, v159
	v_add_u32_e32 v174, s82, v177
	v_add_u32_e32 v175, s83, v244
	s_ashr_i32 s35, s34, 31
	s_lshl_b64 s[36:37], s[34:35], 20
	s_add_u32 s36, s92, s36
	s_addc_u32 s37, s93, s37
	s_ashr_i32 s31, s30, 31
	s_lshl_b64 s[38:39], s[30:31], 20
	s_add_u32 s38, s47, s38
	s_addc_u32 s39, s48, s39
	s_and_b32 s1, s30, -4
	s_cmp_eq_u32 s1, 8
	s_cselect_b32 s1, 1, 0
	s_and_b32 s3, s30, -8
	s_cmp_eq_u32 s3, 24
	s_cselect_b32 s1, 1, s1
	s_cmp_lg_u32 s1, 0
	s_cselect_b32 s1, s38, s36
	s_cselect_b32 s3, s39, s37
	s_cselect_b32 s38, s36, s38
	s_cselect_b32 s39, s37, s39
	s_mov_b32 s36, s1
	s_mov_b32 s37, s3
	s_and_b64 s[44:45], s[4:5], exec
	s_cselect_b32 s1, s37, s41
	s_cselect_b32 s3, s36, s40
	s_cselect_b32 s7, s39, s43
	s_cselect_b32 s10, s38, s42
	s_add_u32 s40, s40, 0x80080
	s_addc_u32 s41, s41, 0
	s_add_u32 s13, s42, 0x100
	s_waitcnt lgkmcnt(0)
	v_mov_b32_e32 v66, 0
	s_addc_u32 s31, s43, 0
	s_mov_b32 s33, -2
	v_mov_b32_e32 v67, v66
	v_mov_b32_e32 v68, v66
	v_mov_b32_e32 v69, v66
	v_mov_b32_e32 v74, v66
	v_mov_b32_e32 v75, v66
	v_mov_b32_e32 v76, v66
	v_mov_b32_e32 v77, v66
	v_mov_b32_e32 v70, v66
	v_mov_b32_e32 v71, v66
	v_mov_b32_e32 v72, v66
	v_mov_b32_e32 v73, v66
	v_mov_b32_e32 v78, v66
	v_mov_b32_e32 v79, v66
	v_mov_b32_e32 v80, v66
	v_mov_b32_e32 v81, v66
	v_mov_b32_e32 v82, v66
	v_mov_b32_e32 v83, v66
	v_mov_b32_e32 v84, v66
	v_mov_b32_e32 v85, v66
	v_mov_b32_e32 v86, v66
	v_mov_b32_e32 v87, v66
	v_mov_b32_e32 v88, v66
	v_mov_b32_e32 v89, v66
	v_mov_b32_e32 v90, v66
	v_mov_b32_e32 v91, v66
	v_mov_b32_e32 v92, v66
	v_mov_b32_e32 v93, v66
	v_mov_b32_e32 v94, v66
	v_mov_b32_e32 v95, v66
	v_mov_b32_e32 v96, v66
	v_mov_b32_e32 v97, v66
	v_mov_b32_e32 v0, v66
	v_mov_b32_e32 v1, v66
	v_mov_b32_e32 v2, v66
	v_mov_b32_e32 v3, v66
	v_mov_b32_e32 v4, v66
	v_mov_b32_e32 v5, v66
	v_mov_b32_e32 v6, v66
	v_mov_b32_e32 v7, v66
	v_mov_b32_e32 v8, v66
	v_mov_b32_e32 v9, v66
	v_mov_b32_e32 v10, v66
	v_mov_b32_e32 v11, v66
	v_mov_b32_e32 v12, v66
	v_mov_b32_e32 v13, v66
	v_mov_b32_e32 v14, v66
	v_mov_b32_e32 v15, v66
	v_mov_b32_e32 v16, v66
	v_mov_b32_e32 v17, v66
	v_mov_b32_e32 v18, v66
	v_mov_b32_e32 v19, v66
	v_mov_b32_e32 v20, v66
	v_mov_b32_e32 v21, v66
	v_mov_b32_e32 v22, v66
	v_mov_b32_e32 v23, v66
	v_mov_b32_e32 v24, v66
	v_mov_b32_e32 v25, v66
	v_mov_b32_e32 v26, v66
	v_mov_b32_e32 v27, v66
	v_mov_b32_e32 v28, v66
	v_mov_b32_e32 v29, v66
	v_mov_b32_e32 v30, v66
	v_mov_b32_e32 v31, v66
	v_mov_b32_e32 v98, v66
	v_mov_b32_e32 v99, v66
	v_mov_b32_e32 v100, v66
	v_mov_b32_e32 v101, v66
	v_mov_b32_e32 v102, v66
	v_mov_b32_e32 v103, v66
	v_mov_b32_e32 v104, v66
	v_mov_b32_e32 v105, v66
	v_mov_b32_e32 v106, v66
	v_mov_b32_e32 v107, v66
	v_mov_b32_e32 v108, v66
	v_mov_b32_e32 v109, v66
	v_mov_b32_e32 v110, v66
	v_mov_b32_e32 v111, v66
	v_mov_b32_e32 v112, v66
	v_mov_b32_e32 v113, v66
	v_mov_b32_e32 v114, v66
	v_mov_b32_e32 v115, v66
	v_mov_b32_e32 v116, v66
	v_mov_b32_e32 v117, v66
	v_mov_b32_e32 v118, v66
	v_mov_b32_e32 v119, v66
	v_mov_b32_e32 v120, v66
	v_mov_b32_e32 v121, v66
	v_mov_b32_e32 v122, v66
	v_mov_b32_e32 v123, v66
	v_mov_b32_e32 v124, v66
	v_mov_b32_e32 v125, v66
	v_mov_b32_e32 v126, v66
	v_mov_b32_e32 v127, v66
	v_mov_b32_e32 v128, v66
	v_mov_b32_e32 v129, v66
	v_mov_b32_e32 v32, v66
	v_mov_b32_e32 v33, v66
	v_mov_b32_e32 v34, v66
	v_mov_b32_e32 v35, v66
	v_mov_b32_e32 v36, v66
	v_mov_b32_e32 v37, v66
	v_mov_b32_e32 v38, v66
	v_mov_b32_e32 v39, v66
	v_mov_b32_e32 v40, v66
	v_mov_b32_e32 v41, v66
	v_mov_b32_e32 v42, v66
	v_mov_b32_e32 v43, v66
	v_mov_b32_e32 v44, v66
	v_mov_b32_e32 v45, v66
	v_mov_b32_e32 v46, v66
	v_mov_b32_e32 v47, v66
	v_mov_b32_e32 v48, v66
	v_mov_b32_e32 v49, v66
	v_mov_b32_e32 v50, v66
	v_mov_b32_e32 v51, v66
	v_mov_b32_e32 v52, v66
	v_mov_b32_e32 v53, v66
	v_mov_b32_e32 v54, v66
	v_mov_b32_e32 v55, v66
	v_mov_b32_e32 v56, v66
	v_mov_b32_e32 v57, v66
	v_mov_b32_e32 v58, v66
	v_mov_b32_e32 v59, v66
	v_mov_b32_e32 v60, v66
	v_mov_b32_e32 v61, v66
	v_mov_b32_e32 v62, v66
	v_mov_b32_e32 v63, v66

; __device__ __forceinline__ unsigned pk2(float lo, float hi) { const f32x2 v = {lo, hi}; const bf16x2_t b = __builtin_convertvector(v, bf16x2_t); return __builtin_bit_cast(unsigned, b); }
;     __device__ __forceinline__ void operator()(const f32x4 (&acc)[2][2][4][2], const pg8::Unit& u, int wr, int wc, int fr, int fq) const {
;     ...
;         const bool tr = (pn >= 8 && pn < 12) || (pn >= 24 && pn < 32);
;         unsigned char* base; int colt, ld;
;         if (pn < 24) { base = ws + WS_AQ + (size_t)(pn >> 2) * SZ1; colt = (pn & 3) * 256; ld = 1024; }
;         else { base = ws + WS_BVT + (size_t)((pn - 24) >> 3) * SZ2; colt = ((pn - 24) & 7) * 256; ld = 2048; }
;         if (tr) {
;             bf16_t* VO = (bf16_t*)base; const bool isb = pn >= 24;
;             bf16_t* T = (bf16_t*)(lds_epi + (wr * 4 + wc) * 2048);
;             const int lane = fq * 16 + fr, col = lane & 31, half = lane >> 5;
; #pragma unroll
;             for (int ai = 0; ai < 2; ++ai)
; #pragma unroll
;                 for (int m = 0; m < 4; ++m)
; #pragma unroll
;                     for (int bj = 0; bj < 2; ++bj) {
; #pragma unroll
;                         for (int n = 0; n < 2; ++n) { const f32x4 v = acc[ai][bj][m][n]; const unsigned w0 = pk2(v[0], v[1]), w1 = pk2(v[2], v[3]);
;                             bf16_t* p = T + (8 * fq + 4 * n) * 24 + fr;
;                             p[0] = (bf16_t)(w0 & 0xffffu); p[24] = (bf16_t)(w0 >> 16); p[48] = (bf16_t)(w1 & 0xffffu); p[72] = (bf16_t)(w1 >> 16); }
;                         asm volatile("s_waitcnt lgkmcnt(0)" ::: "memory");
;                         const u32x4 w = *(const u32x4*)(T + col * 24 + half * 8);
;                         asm volatile("s_waitcnt lgkmcnt(0)" ::: "memory");
;                         const int dvg = colt + bj * 128 + wc * 32 + col;
;                         if (isb) { const size_t gc = (size_t)u.pm * 4 + ai * 2 + wr;
;                             *(u32x4*)(VO + ((((gc * 4 + (dvg >> 9)) * 16 + ((dvg >> 5) & 15)) * 4 + m) * 64 + half * 32 + col) * 8) = w; }
;                         else *(u32x4*)(VO + (size_t)dvg * MR + (size_t)(u.pm * 256 + ai * 128 + wr * 64 + m * 16 + half * 8)) = w;
;                     }
.LBB0_197:
	s_and_b32 s7, s6, -8
	s_cmp_lg_u32 s7, 24
	s_cselect_b64 s[56:57], -1, 0
	s_lshl_b32 s7, s6, 8
	s_and_b32 s10, s3, s7
	s_and_b32 s3, s6, -4
	s_cmp_eq_u32 s3, 8
	s_cselect_b32 s3, s10, s1
	s_cselect_b32 s10, s1, s10
	s_cselect_b32 s42, 0x8200, s42
	v_add_u32_e32 v156, s3, v158
	s_mov_b64 s[44:45], -1
	s_and_b64 vcc, exec, s[56:57]
	v_cvt_pk_bf16_f32 v130, v60, v61
	v_cvt_pk_bf16_f32 v131, v62, v63
	v_cvt_pk_bf16_f32 v132, v56, v57
	v_cvt_pk_bf16_f32 v133, v58, v59
	v_cvt_pk_bf16_f32 v126, v126, v127
	v_cvt_pk_bf16_f32 v127, v128, v129
	v_cvt_pk_bf16_f32 v128, v122, v123
	v_cvt_pk_bf16_f32 v129, v124, v125
	v_cvt_pk_bf16_f32 v122, v52, v53
	v_cvt_pk_bf16_f32 v123, v54, v55
	v_cvt_pk_bf16_f32 v124, v48, v49
	v_cvt_pk_bf16_f32 v125, v50, v51
	v_cvt_pk_bf16_f32 v118, v118, v119
	v_cvt_pk_bf16_f32 v119, v120, v121
	v_cvt_pk_bf16_f32 v120, v114, v115
	v_cvt_pk_bf16_f32 v121, v116, v117
	v_cvt_pk_bf16_f32 v114, v44, v45
	v_cvt_pk_bf16_f32 v115, v46, v47
	v_cvt_pk_bf16_f32 v116, v40, v41
	v_cvt_pk_bf16_f32 v117, v42, v43
	v_cvt_pk_bf16_f32 v110, v110, v111
	v_cvt_pk_bf16_f32 v111, v112, v113
	v_cvt_pk_bf16_f32 v112, v106, v107
	v_cvt_pk_bf16_f32 v113, v108, v109
	v_cvt_pk_bf16_f32 v106, v36, v37
	v_cvt_pk_bf16_f32 v107, v38, v39
	v_cvt_pk_bf16_f32 v108, v32, v33
	v_cvt_pk_bf16_f32 v109, v34, v35
	v_cvt_pk_bf16_f32 v102, v102, v103
	v_cvt_pk_bf16_f32 v103, v104, v105
	v_cvt_pk_bf16_f32 v104, v98, v99
	v_cvt_pk_bf16_f32 v105, v100, v101
	v_cvt_pk_bf16_f32 v98, v28, v29
	v_cvt_pk_bf16_f32 v99, v30, v31
	v_cvt_pk_bf16_f32 v100, v24, v25
	v_cvt_pk_bf16_f32 v101, v26, v27
	v_cvt_pk_bf16_f32 v94, v94, v95
	v_cvt_pk_bf16_f32 v95, v96, v97
	v_cvt_pk_bf16_f32 v96, v90, v91
	v_cvt_pk_bf16_f32 v97, v92, v93
	v_cvt_pk_bf16_f32 v90, v20, v21
	v_cvt_pk_bf16_f32 v91, v22, v23
	v_cvt_pk_bf16_f32 v92, v16, v17
	v_cvt_pk_bf16_f32 v93, v18, v19
	v_cvt_pk_bf16_f32 v86, v86, v87
	v_cvt_pk_bf16_f32 v87, v88, v89
	v_cvt_pk_bf16_f32 v88, v82, v83
	v_cvt_pk_bf16_f32 v89, v84, v85
	v_cvt_pk_bf16_f32 v82, v12, v13
	v_cvt_pk_bf16_f32 v83, v14, v15
	v_cvt_pk_bf16_f32 v84, v8, v9
	v_cvt_pk_bf16_f32 v85, v10, v11
	v_cvt_pk_bf16_f32 v78, v78, v79
	v_cvt_pk_bf16_f32 v79, v80, v81
	v_cvt_pk_bf16_f32 v80, v70, v71
	v_cvt_pk_bf16_f32 v81, v72, v73
	v_cvt_pk_bf16_f32 v70, v4, v5
	v_cvt_pk_bf16_f32 v71, v6, v7
	v_cvt_pk_bf16_f32 v72, v0, v1
	v_cvt_pk_bf16_f32 v73, v2, v3
	v_cvt_pk_bf16_f32 v64, v74, v75
	v_cvt_pk_bf16_f32 v65, v76, v77
	v_cvt_pk_bf16_f32 v66, v66, v67
	v_cvt_pk_bf16_f32 v67, v68, v69
	s_cbranch_vccz .Lp2_bv
	s_and_b32 s32, s0, 3
	s_lshl_b32 s32, s32, 5
	v_add_u32_e32 v68, s32, v162
	v_or_b32_e32 v68, s10, v68
	v_lshlrev_b32_e32 v142, 1, v68
	v_lshl_add_u64 v[68:69], s[40:41], 0, v[142:143]
	v_mad_i64_i32 v[74:75], s[44:45], s42, v156, 0
	v_lshl_add_u64 v[74:75], v[74:75], 1, v[68:69]
	global_store_dwordx4 v[74:75], v[130:133], off nt
	global_store_dwordx4 v[74:75], v[126:129], off offset:64 nt
	v_or_b32_e32 v74, 16, v156
	v_mad_i64_i32 v[74:75], s[44:45], s42, v74, 0
	v_lshl_add_u64 v[74:75], v[74:75], 1, v[68:69]
	global_store_dwordx4 v[74:75], v[122:125], off nt
	global_store_dwordx4 v[74:75], v[118:121], off offset:64 nt
	v_or_b32_e32 v74, 32, v156
	v_mad_i64_i32 v[74:75], s[44:45], s42, v74, 0
	v_lshl_add_u64 v[74:75], v[74:75], 1, v[68:69]
	global_store_dwordx4 v[74:75], v[114:117], off nt
	global_store_dwordx4 v[74:75], v[110:113], off offset:64 nt
	v_or_b32_e32 v74, 48, v156
	v_mad_i64_i32 v[74:75], s[44:45], s42, v74, 0
	v_lshl_add_u64 v[74:75], v[74:75], 1, v[68:69]
	global_store_dwordx4 v[74:75], v[106:109], off nt
	global_store_dwordx4 v[74:75], v[102:105], off offset:64 nt
	v_add_u32_e32 v74, 0x80, v156
	v_mad_i64_i32 v[74:75], s[44:45], s42, v74, 0
	v_lshl_add_u64 v[74:75], v[74:75], 1, v[68:69]
	global_store_dwordx4 v[74:75], v[98:101], off nt
	global_store_dwordx4 v[74:75], v[94:97], off offset:64 nt
	v_add_u32_e32 v74, 0x90, v156
	v_mad_i64_i32 v[74:75], s[44:45], s42, v74, 0
	v_lshl_add_u64 v[74:75], v[74:75], 1, v[68:69]
	global_store_dwordx4 v[74:75], v[90:93], off nt
	global_store_dwordx4 v[74:75], v[86:89], off offset:64 nt
	v_add_u32_e32 v74, 0xa0, v156
	v_mad_i64_i32 v[74:75], s[44:45], s42, v74, 0
	v_lshl_add_u64 v[74:75], v[74:75], 1, v[68:69]
	global_store_dwordx4 v[74:75], v[82:85], off nt
	global_store_dwordx4 v[74:75], v[78:81], off offset:64 nt
	v_add_u32_e32 v74, 0xb0, v156
	v_mad_i64_i32 v[74:75], s[42:43], s42, v74, 0
	v_lshl_add_u64 v[68:69], v[74:75], 1, v[68:69]
	global_store_dwordx4 v[68:69], v[70:73], off nt
	global_store_dwordx4 v[68:69], v[64:67], off offset:64 nt
	s_mov_b64 s[44:45], 0
	s_branch .LBB0_199
.Lp2_bv:
	s_lshl_b32 s3, s12, 20
	s_and_b32 s7, s0, 3
	s_lshl_b32 s7, s7, 18
	s_add_u32 s3, s3, s7
	s_sub_i32 s7, s6, 24
	s_and_b32 s7, s7, 7
	s_lshr_b32 s32, s7, 1
	s_lshl_b32 s32, s32, 16
	s_add_u32 s3, s3, s32
	s_and_b32 s7, s7, 1
	s_lshl_b32 s7, s7, 15
	s_add_u32 s3, s3, s7
	s_bfe_u32 s7, s0, 0x10002
	s_lshl_b32 s7, s7, 13
	s_add_u32 s3, s3, s7
	s_add_u32 s40, s40, s3
	s_addc_u32 s41, s41, 0
	v_lshrrev_b32_e32 v68, 4, v160
	v_and_b32_e32 v74, 15, v160
	v_lshlrev_b32_e32 v68, 9, v68
	v_lshl_or_b32 v68, v74, 4, v68
	v_mov_b32_e32 v69, 0
	v_lshl_add_u64 v[68:69], s[40:41], 0, v[68:69]
	s_mov_b64 s[56:57], 0x1000
	v_lshl_add_u64 v[246:247], v[68:69], 0, s[56:57]
	s_mov_b64 s[56:57], 0x4000
	v_lshl_add_u64 v[248:249], v[68:69], 0, s[56:57]
	s_mov_b64 s[56:57], 0x5000
	v_lshl_add_u64 v[250:251], v[68:69], 0, s[56:57]
	global_store_dwordx4 v[68:69], v[130:133], off nt
	global_store_dwordx4 v[68:69], v[126:129], off offset:2048 nt
	global_store_dwordx4 v[68:69], v[122:125], off offset:256 nt
	global_store_dwordx4 v[68:69], v[118:121], off offset:2304 nt
	global_store_dwordx4 v[246:247], v[114:117], off nt
	global_store_dwordx4 v[246:247], v[110:113], off offset:2048 nt
	global_store_dwordx4 v[246:247], v[106:109], off offset:256 nt
	global_store_dwordx4 v[246:247], v[102:105], off offset:2304 nt
	global_store_dwordx4 v[248:249], v[98:101], off nt
	global_store_dwordx4 v[248:249], v[94:97], off offset:2048 nt
	global_store_dwordx4 v[248:249], v[90:93], off offset:256 nt
	global_store_dwordx4 v[248:249], v[86:89], off offset:2304 nt
	global_store_dwordx4 v[250:251], v[82:85], off nt
	global_store_dwordx4 v[250:251], v[78:81], off offset:2048 nt
	global_store_dwordx4 v[250:251], v[70:73], off offset:256 nt
	global_store_dwordx4 v[250:251], v[64:67], off offset:2304 nt
	s_mov_b64 s[44:45], 0
